# PLEGATE epilogue: counted vmcnt waits (4/10) instead of vmcnt(0) drains
# speedup vs baseline: 1.0087x; 1.0018x over previous
; template <int EPI>
; __device__ __forceinline__ void gemm_epilogue(const f32x4 (&acc)[2][2][4][2], const Unit& u, int wr, int wc, int fr, int fq,
;                                               const EpiArgs& ea, const float (&rs_pre)[2][4]) {
;     ...
;         for (int m = 0; m < 4; ++m) rper[ai][m] = ea.aux_f0[row0 + ai * 128 + m * 16];
; #pragma unroll
;       for (int ai = 0; ai < 2; ++ai)
; #pragma unroll
;         for (int m = 0; m < 4; ++m) rper[ai][m] = rstd_of(rper[ai][m]);
;     ...
;     EPI_LOAD_ROW(0, hc, lc, pc);
; #pragma unroll
;     for (int it = 0; it < 8; ++it) {
;       const int ai = it >> 2, m = it & 3;
;       if (it + 1 < 8) EPI_LOAD_ROW(it + 1, hn, ln_, pq);
;       const int row = row0 + ai * 128 + m * 16;
;       float sq = 0.f;
; #pragma unroll
;       for (int bj = 0; bj < 2; ++bj) {
;         const size_t idx = (size_t)row * 1024 + lcp + bj * 32;
;         const uint32_t hw[4] = {hc[bj].x, hc[bj].y, hc[bj].z, hc[bj].w};
;         const uint32_t lw[4] = {lc[bj].x, lc[bj].y, lc[bj].z, lc[bj].w};
;         const uint32_t pw[4] = {pc[bj].x, pc[bj].y, pc[bj].z, pc[bj].w};
;         uint32_t ho[4], lo_[4];
; #pragma unroll
;         for (int n = 0; n < 2; ++n) {
;           f32x4 xv;
;           xv[0] = __uint_as_float(hw[2 * n] << 16) + __uint_as_float(lw[2 * n] << 16);
;           xv[1] = __uint_as_float(hw[2 * n] & 0xffff0000u) + __uint_as_float(lw[2 * n] & 0xffff0000u);
;           xv[2] = __uint_as_float(hw[2 * n + 1] << 16) + __uint_as_float(lw[2 * n + 1] << 16);
;           xv[3] = __uint_as_float(hw[2 * n + 1] & 0xffff0000u) + __uint_as_float(lw[2 * n + 1] & 0xffff0000u);
;           const f32x4 a = acc[ai][bj][m][n];
;           f32x4 v;
;           if constexpr (EPI == EPI_PLEGATE) {
;             const float rs = rsr[ai][m], rpe = rper[ai][m];
;             const float pv[4] = {__uint_as_float(pw[2 * n] << 16), __uint_as_float(pw[2 * n] & 0xffff0000u),
;                                  __uint_as_float(pw[2 * n + 1] << 16), __uint_as_float(pw[2 * n + 1] & 0xffff0000u)};
; #pragma unroll
;             for (int i = 0; i < 4; ++i) v[i] = xv[i] + sigmoidf_(a[i] * rs) * (pv[i] * rpe);
;           } else {
;             v = xv + a * ea.alpha;
;           }
;           const uint2 hnew = pack4(v);
;           ho[2 * n] = hnew.x; ho[2 * n + 1] = hnew.y;
;           if (ea.xf32_out) {
.LBB0_223:
	s_or_b64 exec, exec, s[8:9]
	v_or_b32_e32 v144, 48, v196
	v_ashrrev_i32_e32 v145, 31, v144
	v_lshlrev_b64 v[100:101], 10, v[144:145]
	v_lshl_add_u64 v[148:149], v[100:101], 0, v[194:195]
	v_lshlrev_b64 v[146:147], 1, v[148:149]
	v_readlane_b32 s8, v251, 32
	v_lshl_add_u64 v[100:101], s[46:47], 0, v[146:147]
	v_lshl_add_u64 v[102:103], s[18:19], 0, v[146:147]
	v_readlane_b32 s9, v251, 33
	v_fmamk_f32 v113, v217, 0x3a800000, v218
	v_cmp_gt_f32_e32 vcc, s26, v113
	v_lshl_add_u64 v[118:119], s[8:9], 0, v[146:147]
	global_load_dwordx4 v[132:135], v[100:101], off
	global_load_dwordx4 v[104:107], v[100:101], off offset:64
	global_load_dwordx4 v[136:139], v[102:103], off
	global_load_dwordx4 v[108:111], v[102:103], off offset:64
	global_load_dwordx4 v[114:117], v[118:119], off
	s_nop 0
	global_load_dwordx4 v[100:103], v[118:119], off offset:64
	v_mul_f32_e32 v118, 0x4b800000, v113
	v_cndmask_b32_e32 v113, v113, v118, vcc
	v_fmamk_f32 v118, v239, 0x3a800000, v218
	v_rsq_f32_e32 v113, v113
	v_mul_f32_e32 v119, 0x4b800000, v118
	v_cmp_gt_f32_e64 s[8:9], s26, v118
	s_waitcnt vmcnt(10)
	v_lshlrev_b32_e32 v140, 16, v164
	v_and_b32_e32 v141, 0xffff0000, v164
	v_cndmask_b32_e64 v118, v118, v119, s[8:9]
	v_rsq_f32_e32 v118, v118
	v_mul_f32_e32 v119, 0x45800000, v113
	v_cndmask_b32_e32 v113, v113, v119, vcc
	v_mul_f32_e32 v98, v113, v98
	v_mul_f32_e32 v119, 0x45800000, v118
	v_cndmask_b32_e64 v150, v118, v119, s[8:9]
	v_lshlrev_b32_e32 v118, 16, v160
	v_and_b32_e32 v119, 0xffff0000, v160
	v_mul_f32_e32 v96, v113, v96
	v_mul_f32_e32 v97, v113, v97
	v_mul_f32_e32 v98, 0xbfb8aa3b, v98
	v_mul_f32_e32 v96, 0xbfb8aa3b, v96
	v_mul_f32_e32 v97, 0xbfb8aa3b, v97
	v_pk_add_f32 v[118:119], v[118:119], v[140:141]
	v_exp_f32_e32 v140, v98
	v_mul_f32_e32 v98, v113, v99
	v_exp_f32_e32 v96, v96
	v_exp_f32_e32 v97, v97
	v_mul_f32_e32 v98, 0xbfb8aa3b, v98
	v_exp_f32_e32 v141, v98
	v_add_f32_e32 v96, 1.0, v96
	v_add_f32_e32 v97, 1.0, v97
	v_rcp_f32_e32 v96, v96
	v_rcp_f32_e32 v97, v97
	v_add_f32_e32 v140, 1.0, v140
	v_add_f32_e32 v141, 1.0, v141
	v_rcp_f32_e32 v140, v140
	v_rcp_f32_e32 v141, v141
	v_lshlrev_b32_e32 v154, 16, v156
	v_and_b32_e32 v155, 0xffff0000, v156
	v_lshlrev_b32_e32 v142, 16, v161
	v_lshlrev_b32_e32 v152, 16, v165
	v_and_b32_e32 v143, 0xffff0000, v161
	v_and_b32_e32 v153, 0xffff0000, v165
	v_lshlrev_b32_e32 v156, 16, v157
	v_and_b32_e32 v157, 0xffff0000, v157
	v_pk_mul_f32 v[98:99], v[150:151], v[154:155] op_sel_hi:[0,1]
	v_pk_fma_f32 v[96:97], v[96:97], v[98:99], v[118:119]
	v_pk_add_f32 v[98:99], v[142:143], v[152:153]
	v_pk_mul_f32 v[118:119], v[150:151], v[156:157] op_sel_hi:[0,1]
	v_pk_fma_f32 v[98:99], v[140:141], v[118:119], v[98:99]
	s_and_b64 vcc, exec, s[4:5]
	s_mov_b64 s[36:37], -1
	v_cvt_pk_bf16_f32 v140, v96, v97
	v_cvt_pk_bf16_f32 v141, v98, v99
	s_cbranch_vccnz .LBB0_225
	v_lshl_add_u64 v[118:119], v[172:173], 2, s[88:89]
	s_mov_b64 s[36:37], 0
	s_mov_b64 s[8:9], s[88:89]
	global_store_dwordx4 v[118:119], v[96:99], off

; template <int EPI>
; __device__ __forceinline__ void gemm_epilogue(const f32x4 (&acc)[2][2][4][2], const Unit& u, int wr, int wc, int fr, int fq,
;                                               const EpiArgs& ea, const float (&rs_pre)[2][4]) {
;     ...
;         for (int m = 0; m < 4; ++m) rper[ai][m] = ea.aux_f0[row0 + ai * 128 + m * 16];
; #pragma unroll
;       for (int ai = 0; ai < 2; ++ai)
; #pragma unroll
;         for (int m = 0; m < 4; ++m) rper[ai][m] = rstd_of(rper[ai][m]);
;     ...
;     EPI_LOAD_ROW(0, hc, lc, pc);
; #pragma unroll
;     for (int it = 0; it < 8; ++it) {
;       const int ai = it >> 2, m = it & 3;
;       if (it + 1 < 8) EPI_LOAD_ROW(it + 1, hn, ln_, pq);
;       const int row = row0 + ai * 128 + m * 16;
;       float sq = 0.f;
; #pragma unroll
;       for (int bj = 0; bj < 2; ++bj) {
;         const size_t idx = (size_t)row * 1024 + lcp + bj * 32;
;         const uint32_t hw[4] = {hc[bj].x, hc[bj].y, hc[bj].z, hc[bj].w};
;         const uint32_t lw[4] = {lc[bj].x, lc[bj].y, lc[bj].z, lc[bj].w};
;         const uint32_t pw[4] = {pc[bj].x, pc[bj].y, pc[bj].z, pc[bj].w};
;         uint32_t ho[4], lo_[4];
; #pragma unroll
;         for (int n = 0; n < 2; ++n) {
;           f32x4 xv;
;           xv[0] = __uint_as_float(hw[2 * n] << 16) + __uint_as_float(lw[2 * n] << 16);
;           xv[1] = __uint_as_float(hw[2 * n] & 0xffff0000u) + __uint_as_float(lw[2 * n] & 0xffff0000u);
;           xv[2] = __uint_as_float(hw[2 * n + 1] << 16) + __uint_as_float(lw[2 * n + 1] << 16);
;           xv[3] = __uint_as_float(hw[2 * n + 1] & 0xffff0000u) + __uint_as_float(lw[2 * n + 1] & 0xffff0000u);
;           const f32x4 a = acc[ai][bj][m][n];
;           f32x4 v;
;           if constexpr (EPI == EPI_PLEGATE) {
;             const float rs = rsr[ai][m], rpe = rper[ai][m];
;             const float pv[4] = {__uint_as_float(pw[2 * n] << 16), __uint_as_float(pw[2 * n] & 0xffff0000u),
;                                  __uint_as_float(pw[2 * n + 1] << 16), __uint_as_float(pw[2 * n + 1] & 0xffff0000u)};
; #pragma unroll
;             for (int i = 0; i < 4; ++i) v[i] = xv[i] + sigmoidf_(a[i] * rs) * (pv[i] * rpe);
;           } else {
;             v = xv + a * ea.alpha;
;           }
;           const uint2 hnew = pack4(v);
;           ho[2 * n] = hnew.x; ho[2 * n + 1] = hnew.y;
;           if (ea.xf32_out) {
.LBB0_246:
	s_waitcnt vmcnt(4)
	s_or_b64 exec, exec, s[8:9]
	v_add_u32_e32 v126, 0x80, v196
	v_ashrrev_i32_e32 v127, 31, v126
	v_lshlrev_b64 v[84:85], 10, v[126:127]
	v_lshl_add_u64 v[130:131], v[84:85], 0, v[194:195]
	v_lshlrev_b64 v[128:129], 1, v[130:131]
	v_readlane_b32 s8, v251, 32
	v_lshl_add_u64 v[84:85], s[46:47], 0, v[128:129]
	v_lshl_add_u64 v[86:87], s[18:19], 0, v[128:129]
	v_readlane_b32 s9, v251, 33
	v_fmamk_f32 v113, v215, 0x3a800000, v218
	v_cmp_gt_f32_e32 vcc, s26, v113
	v_lshl_add_u64 v[140:141], s[8:9], 0, v[128:129]
	global_load_dwordx4 v[118:121], v[84:85], off
	global_load_dwordx4 v[88:91], v[84:85], off offset:64
	global_load_dwordx4 v[122:125], v[86:87], off
	global_load_dwordx4 v[92:95], v[86:87], off offset:64
	global_load_dwordx4 v[96:99], v[140:141], off
	s_nop 0
	global_load_dwordx4 v[84:87], v[140:141], off offset:64
	v_mul_f32_e32 v140, 0x4b800000, v113
	v_cndmask_b32_e32 v113, v113, v140, vcc
	v_rsq_f32_e32 v113, v113
	v_fmamk_f32 v140, v238, 0x3a800000, v218
	v_mul_f32_e32 v141, 0x4b800000, v140
	v_cmp_gt_f32_e64 s[8:9], s26, v140
	v_lshlrev_b32_e32 v142, 16, v132
	v_lshlrev_b32_e32 v150, 16, v136
	v_cndmask_b32_e64 v140, v140, v141, s[8:9]
	v_rsq_f32_e32 v140, v140
	v_mul_f32_e32 v141, 0x45800000, v113
	v_cndmask_b32_e32 v113, v113, v141, vcc
	v_mul_f32_e32 v82, v113, v82
	v_mul_f32_e32 v141, 0x45800000, v140
	v_mul_f32_e32 v80, v113, v80
	v_mul_f32_e32 v81, v113, v81
	v_mul_f32_e32 v82, 0xbfb8aa3b, v82
	v_cndmask_b32_e64 v140, v140, v141, s[8:9]
	v_mul_f32_e32 v80, 0xbfb8aa3b, v80
	v_mul_f32_e32 v81, 0xbfb8aa3b, v81
	v_exp_f32_e32 v141, v82
	v_mul_f32_e32 v82, v113, v83
	v_and_b32_e32 v143, 0xffff0000, v132
	v_and_b32_e32 v151, 0xffff0000, v136
	v_exp_f32_e32 v80, v80
	v_exp_f32_e32 v81, v81
	v_mul_f32_e32 v82, 0xbfb8aa3b, v82
	v_pk_add_f32 v[142:143], v[142:143], v[150:151]
	v_exp_f32_e32 v151, v82
	v_lshlrev_b32_e32 v152, 16, v114
	v_and_b32_e32 v153, 0xffff0000, v114
	v_add_f32_e32 v80, 1.0, v80
	v_add_f32_e32 v81, 1.0, v81
	v_pk_mul_f32 v[82:83], v[140:141], v[152:153] op_sel_hi:[0,1]
	v_add_f32_e32 v141, 1.0, v141
	v_rcp_f32_e32 v80, v80
	v_rcp_f32_e32 v81, v81
	v_rcp_f32_e32 v150, v141
	v_add_f32_e32 v141, 1.0, v151
	v_rcp_f32_e32 v151, v141
	v_lshlrev_b32_e32 v132, 16, v133
	v_lshlrev_b32_e32 v136, 16, v137
	v_and_b32_e32 v133, 0xffff0000, v133
	v_and_b32_e32 v137, 0xffff0000, v137
	v_lshlrev_b32_e32 v114, 16, v115
	v_and_b32_e32 v115, 0xffff0000, v115
	v_pk_fma_f32 v[80:81], v[80:81], v[82:83], v[142:143]
	v_pk_add_f32 v[82:83], v[132:133], v[136:137]
	v_pk_mul_f32 v[114:115], v[140:141], v[114:115] op_sel_hi:[0,1]
	v_pk_fma_f32 v[82:83], v[150:151], v[114:115], v[82:83]
	s_and_b64 vcc, exec, s[4:5]
	s_mov_b64 s[36:37], -1
	v_cvt_pk_bf16_f32 v114, v80, v81
	v_cvt_pk_bf16_f32 v115, v82, v83
	s_cbranch_vccnz .LBB0_248
	v_lshl_add_u64 v[132:133], v[148:149], 2, s[88:89]
	s_mov_b64 s[36:37], 0
	s_mov_b64 s[8:9], s[88:89]
	global_store_dwordx4 v[132:133], v[80:83], off

; template <int EPI>
; __device__ __forceinline__ void gemm_epilogue(const f32x4 (&acc)[2][2][4][2], const Unit& u, int wr, int wc, int fr, int fq,
;                                               const EpiArgs& ea, const float (&rs_pre)[2][4]) {
;     ...
;         for (int m = 0; m < 4; ++m) rper[ai][m] = ea.aux_f0[row0 + ai * 128 + m * 16];
; #pragma unroll
;       for (int ai = 0; ai < 2; ++ai)
; #pragma unroll
;         for (int m = 0; m < 4; ++m) rper[ai][m] = rstd_of(rper[ai][m]);
;     ...
;     EPI_LOAD_ROW(0, hc, lc, pc);
; #pragma unroll
;     for (int it = 0; it < 8; ++it) {
;       const int ai = it >> 2, m = it & 3;
;       if (it + 1 < 8) EPI_LOAD_ROW(it + 1, hn, ln_, pq);
;       const int row = row0 + ai * 128 + m * 16;
;       float sq = 0.f;
; #pragma unroll
;       for (int bj = 0; bj < 2; ++bj) {
;         const size_t idx = (size_t)row * 1024 + lcp + bj * 32;
;         const uint32_t hw[4] = {hc[bj].x, hc[bj].y, hc[bj].z, hc[bj].w};
;         const uint32_t lw[4] = {lc[bj].x, lc[bj].y, lc[bj].z, lc[bj].w};
;         const uint32_t pw[4] = {pc[bj].x, pc[bj].y, pc[bj].z, pc[bj].w};
;         uint32_t ho[4], lo_[4];
; #pragma unroll
;         for (int n = 0; n < 2; ++n) {
;           f32x4 xv;
;           xv[0] = __uint_as_float(hw[2 * n] << 16) + __uint_as_float(lw[2 * n] << 16);
;           xv[1] = __uint_as_float(hw[2 * n] & 0xffff0000u) + __uint_as_float(lw[2 * n] & 0xffff0000u);
;           xv[2] = __uint_as_float(hw[2 * n + 1] << 16) + __uint_as_float(lw[2 * n + 1] << 16);
;           xv[3] = __uint_as_float(hw[2 * n + 1] & 0xffff0000u) + __uint_as_float(lw[2 * n + 1] & 0xffff0000u);
;           const f32x4 a = acc[ai][bj][m][n];
;           f32x4 v;
;           if constexpr (EPI == EPI_PLEGATE) {
;             const float rs = rsr[ai][m], rpe = rper[ai][m];
;             const float pv[4] = {__uint_as_float(pw[2 * n] << 16), __uint_as_float(pw[2 * n] & 0xffff0000u),
;                                  __uint_as_float(pw[2 * n + 1] << 16), __uint_as_float(pw[2 * n + 1] & 0xffff0000u)};
; #pragma unroll
;             for (int i = 0; i < 4; ++i) v[i] = xv[i] + sigmoidf_(a[i] * rs) * (pv[i] * rpe);
;           } else {
;             v = xv + a * ea.alpha;
;           }
;           const uint2 hnew = pack4(v);
;           ho[2 * n] = hnew.x; ho[2 * n + 1] = hnew.y;
;           if (ea.xf32_out) {
.LBB0_269:
	s_or_b64 exec, exec, s[8:9]
	v_or_b32_e32 v108, 16, v126
	v_ashrrev_i32_e32 v109, 31, v108
	v_lshlrev_b64 v[68:69], 10, v[108:109]
	v_lshl_add_u64 v[114:115], v[68:69], 0, v[194:195]
	v_lshlrev_b64 v[110:111], 1, v[114:115]
	v_readlane_b32 s8, v251, 32
	v_lshl_add_u64 v[68:69], s[46:47], 0, v[110:111]
	v_lshl_add_u64 v[70:71], s[18:19], 0, v[110:111]
	v_readlane_b32 s9, v251, 33
	v_fmamk_f32 v113, v213, 0x3a800000, v218
	v_cmp_gt_f32_e32 vcc, s26, v113
	v_lshl_add_u64 v[116:117], s[8:9], 0, v[110:111]
	global_load_dwordx4 v[100:103], v[68:69], off
	global_load_dwordx4 v[72:75], v[68:69], off offset:64
	global_load_dwordx4 v[104:107], v[70:71], off
	global_load_dwordx4 v[76:79], v[70:71], off offset:64
	global_load_dwordx4 v[80:83], v[116:117], off
	s_nop 0
	global_load_dwordx4 v[68:71], v[116:117], off offset:64
	v_mul_f32_e32 v116, 0x4b800000, v113
	v_cndmask_b32_e32 v113, v113, v116, vcc
	v_rsq_f32_e32 v113, v113
	v_fmamk_f32 v116, v237, 0x3a800000, v218
	v_mul_f32_e32 v117, 0x4b800000, v116
	v_cmp_gt_f32_e64 s[8:9], s26, v116
	s_waitcnt vmcnt(10)
	v_lshlrev_b32_e32 v132, 16, v118
	v_lshlrev_b32_e32 v134, 16, v122
	v_cndmask_b32_e64 v116, v116, v117, s[8:9]
	v_rsq_f32_e32 v116, v116
	v_mul_f32_e32 v117, 0x45800000, v113
	v_cndmask_b32_e32 v113, v113, v117, vcc
	v_mul_f32_e32 v66, v113, v66
	v_mul_f32_e32 v117, 0x45800000, v116
	v_mul_f32_e32 v64, v113, v64
	v_mul_f32_e32 v65, v113, v65
	v_mul_f32_e32 v66, 0xbfb8aa3b, v66
	v_cndmask_b32_e64 v116, v116, v117, s[8:9]
	v_mul_f32_e32 v64, 0xbfb8aa3b, v64
	v_mul_f32_e32 v65, 0xbfb8aa3b, v65
	v_exp_f32_e32 v117, v66
	v_mul_f32_e32 v66, v113, v67
	v_and_b32_e32 v133, 0xffff0000, v118
	v_and_b32_e32 v135, 0xffff0000, v122
	v_exp_f32_e32 v64, v64
	v_exp_f32_e32 v65, v65
	v_mul_f32_e32 v66, 0xbfb8aa3b, v66
	v_pk_add_f32 v[132:133], v[132:133], v[134:135]
	v_exp_f32_e32 v135, v66
	v_lshlrev_b32_e32 v136, 16, v96
	v_and_b32_e32 v137, 0xffff0000, v96
	v_add_f32_e32 v64, 1.0, v64
	v_add_f32_e32 v65, 1.0, v65
	v_pk_mul_f32 v[66:67], v[116:117], v[136:137] op_sel_hi:[0,1]
	v_add_f32_e32 v117, 1.0, v117
	v_rcp_f32_e32 v64, v64
	v_rcp_f32_e32 v65, v65
	v_rcp_f32_e32 v134, v117
	v_add_f32_e32 v117, 1.0, v135
	v_rcp_f32_e32 v135, v117
	v_lshlrev_b32_e32 v118, 16, v119
	v_lshlrev_b32_e32 v122, 16, v123
	v_and_b32_e32 v119, 0xffff0000, v119
	v_and_b32_e32 v123, 0xffff0000, v123
	v_lshlrev_b32_e32 v96, 16, v97
	v_and_b32_e32 v97, 0xffff0000, v97
	v_pk_fma_f32 v[64:65], v[64:65], v[66:67], v[132:133]
	v_pk_add_f32 v[66:67], v[118:119], v[122:123]
	v_pk_mul_f32 v[96:97], v[116:117], v[96:97] op_sel_hi:[0,1]
	v_pk_fma_f32 v[66:67], v[134:135], v[96:97], v[66:67]
	s_and_b64 vcc, exec, s[4:5]
	s_mov_b64 s[36:37], -1
	v_cvt_pk_bf16_f32 v96, v64, v65
	v_cvt_pk_bf16_f32 v97, v66, v67
	s_cbranch_vccnz .LBB0_271
	v_lshl_add_u64 v[118:119], v[130:131], 2, s[88:89]
	s_mov_b64 s[36:37], 0
	s_mov_b64 s[8:9], s[88:89]
	global_store_dwordx4 v[118:119], v[64:67], off

; template <int EPI>
; __device__ __forceinline__ void gemm_epilogue(const f32x4 (&acc)[2][2][4][2], const Unit& u, int wr, int wc, int fr, int fq,
;                                               const EpiArgs& ea, const float (&rs_pre)[2][4]) {
;     ...
;         for (int m = 0; m < 4; ++m) rper[ai][m] = ea.aux_f0[row0 + ai * 128 + m * 16];
; #pragma unroll
;       for (int ai = 0; ai < 2; ++ai)
; #pragma unroll
;         for (int m = 0; m < 4; ++m) rper[ai][m] = rstd_of(rper[ai][m]);
;     ...
;     EPI_LOAD_ROW(0, hc, lc, pc);
; #pragma unroll
;     for (int it = 0; it < 8; ++it) {
;       const int ai = it >> 2, m = it & 3;
;       if (it + 1 < 8) EPI_LOAD_ROW(it + 1, hn, ln_, pq);
;       const int row = row0 + ai * 128 + m * 16;
;       float sq = 0.f;
; #pragma unroll
;       for (int bj = 0; bj < 2; ++bj) {
;         const size_t idx = (size_t)row * 1024 + lcp + bj * 32;
;         const uint32_t hw[4] = {hc[bj].x, hc[bj].y, hc[bj].z, hc[bj].w};
;         const uint32_t lw[4] = {lc[bj].x, lc[bj].y, lc[bj].z, lc[bj].w};
;         const uint32_t pw[4] = {pc[bj].x, pc[bj].y, pc[bj].z, pc[bj].w};
;         uint32_t ho[4], lo_[4];
; #pragma unroll
;         for (int n = 0; n < 2; ++n) {
;           f32x4 xv;
;           xv[0] = __uint_as_float(hw[2 * n] << 16) + __uint_as_float(lw[2 * n] << 16);
;           xv[1] = __uint_as_float(hw[2 * n] & 0xffff0000u) + __uint_as_float(lw[2 * n] & 0xffff0000u);
;           xv[2] = __uint_as_float(hw[2 * n + 1] << 16) + __uint_as_float(lw[2 * n + 1] << 16);
;           xv[3] = __uint_as_float(hw[2 * n + 1] & 0xffff0000u) + __uint_as_float(lw[2 * n + 1] & 0xffff0000u);
;           const f32x4 a = acc[ai][bj][m][n];
;           f32x4 v;
;           if constexpr (EPI == EPI_PLEGATE) {
;             const float rs = rsr[ai][m], rpe = rper[ai][m];
;             const float pv[4] = {__uint_as_float(pw[2 * n] << 16), __uint_as_float(pw[2 * n] & 0xffff0000u),
;                                  __uint_as_float(pw[2 * n + 1] << 16), __uint_as_float(pw[2 * n + 1] & 0xffff0000u)};
; #pragma unroll
;             for (int i = 0; i < 4; ++i) v[i] = xv[i] + sigmoidf_(a[i] * rs) * (pv[i] * rpe);
;           } else {
;             v = xv + a * ea.alpha;
;           }
;           const uint2 hnew = pack4(v);
;           ho[2 * n] = hnew.x; ho[2 * n + 1] = hnew.y;
;           if (ea.xf32_out) {
.LBB0_292:
	s_waitcnt vmcnt(4)
	s_or_b64 exec, exec, s[8:9]
	v_or_b32_e32 v96, 32, v126
	v_ashrrev_i32_e32 v97, 31, v96
	v_lshlrev_b64 v[52:53], 10, v[96:97]
	v_lshl_add_u64 v[116:117], v[52:53], 0, v[194:195]
	v_lshlrev_b64 v[98:99], 1, v[116:117]
	v_readlane_b32 s8, v251, 32
	v_lshl_add_u64 v[52:53], s[46:47], 0, v[98:99]
	v_lshl_add_u64 v[54:55], s[18:19], 0, v[98:99]
	v_readlane_b32 s9, v251, 33
	v_and_b32_e32 v67, 0xffff0000, v104
	v_lshlrev_b32_e32 v120, 16, v80
	v_lshl_add_u64 v[64:65], s[8:9], 0, v[98:99]
	global_load_dwordx4 v[88:91], v[52:53], off
	global_load_dwordx4 v[56:59], v[52:53], off offset:64
	global_load_dwordx4 v[92:95], v[54:55], off
	global_load_dwordx4 v[60:63], v[54:55], off offset:64
	global_load_dwordx4 v[84:87], v[64:65], off
	s_nop 0
	global_load_dwordx4 v[52:55], v[64:65], off offset:64
	v_fmamk_f32 v64, v212, 0x3a800000, v218
	v_mul_f32_e32 v65, 0x4b800000, v64
	v_cmp_gt_f32_e32 vcc, s26, v64
	v_and_b32_e32 v121, 0xffff0000, v80
	v_lshlrev_b32_e32 v80, 16, v81
	v_cndmask_b32_e32 v64, v64, v65, vcc
	v_fmamk_f32 v65, v235, 0x3a800000, v218
	v_rsq_f32_e32 v64, v64
	v_mul_f32_e32 v66, 0x4b800000, v65
	v_cmp_gt_f32_e64 s[8:9], s26, v65
	v_and_b32_e32 v81, 0xffff0000, v81
	s_mov_b64 s[36:37], -1
	v_cndmask_b32_e64 v65, v65, v66, s[8:9]
	v_rsq_f32_e32 v65, v65
	v_mul_f32_e32 v66, 0x45800000, v64
	v_cndmask_b32_e32 v113, v64, v66, vcc
	v_mul_f32_e32 v50, v113, v50
	v_mul_f32_e32 v64, 0x45800000, v65
	v_cndmask_b32_e64 v118, v65, v64, s[8:9]
	v_lshlrev_b32_e32 v64, 16, v100
	v_lshlrev_b32_e32 v66, 16, v104
	v_and_b32_e32 v65, 0xffff0000, v100
	v_mul_f32_e32 v48, v113, v48
	v_mul_f32_e32 v49, v113, v49
	v_mul_f32_e32 v50, 0xbfb8aa3b, v50
	v_mul_f32_e32 v48, 0xbfb8aa3b, v48
	v_mul_f32_e32 v49, 0xbfb8aa3b, v49
	v_pk_add_f32 v[64:65], v[64:65], v[66:67]
	v_exp_f32_e32 v66, v50
	v_mul_f32_e32 v50, v113, v51
	v_exp_f32_e32 v48, v48
	v_exp_f32_e32 v49, v49
	v_mul_f32_e32 v50, 0xbfb8aa3b, v50
	v_exp_f32_e32 v67, v50
	v_add_f32_e32 v48, 1.0, v48
	v_add_f32_e32 v49, 1.0, v49
	v_rcp_f32_e32 v48, v48
	v_rcp_f32_e32 v49, v49
	v_add_f32_e32 v66, 1.0, v66
	v_add_f32_e32 v67, 1.0, v67
	v_rcp_f32_e32 v66, v66
	v_rcp_f32_e32 v67, v67
	v_lshlrev_b32_e32 v100, 16, v101
	v_lshlrev_b32_e32 v104, 16, v105
	v_and_b32_e32 v101, 0xffff0000, v101
	v_and_b32_e32 v105, 0xffff0000, v105
	v_pk_mul_f32 v[50:51], v[118:119], v[120:121] op_sel_hi:[0,1]
	v_pk_fma_f32 v[48:49], v[48:49], v[50:51], v[64:65]
	v_pk_add_f32 v[50:51], v[100:101], v[104:105]
	v_pk_mul_f32 v[64:65], v[118:119], v[80:81] op_sel_hi:[0,1]
	v_pk_fma_f32 v[50:51], v[66:67], v[64:65], v[50:51]
	s_and_b64 vcc, exec, s[4:5]
	v_cvt_pk_bf16_f32 v64, v48, v49
	v_cvt_pk_bf16_f32 v65, v50, v51
	s_cbranch_vccnz .LBB0_294
	v_lshl_add_u64 v[66:67], v[114:115], 2, s[88:89]
	s_mov_b64 s[36:37], 0
	s_mov_b64 s[8:9], s[88:89]
	global_store_dwordx4 v[66:67], v[48:51], off

; template <int EPI>
; __device__ __forceinline__ void gemm_epilogue(const f32x4 (&acc)[2][2][4][2], const Unit& u, int wr, int wc, int fr, int fq,
;                                               const EpiArgs& ea, const float (&rs_pre)[2][4]) {
;     ...
;         for (int m = 0; m < 4; ++m) rper[ai][m] = ea.aux_f0[row0 + ai * 128 + m * 16];
; #pragma unroll
;       for (int ai = 0; ai < 2; ++ai)
; #pragma unroll
;         for (int m = 0; m < 4; ++m) rper[ai][m] = rstd_of(rper[ai][m]);
;     ...
;     EPI_LOAD_ROW(0, hc, lc, pc);
; #pragma unroll
;     for (int it = 0; it < 8; ++it) {
;       const int ai = it >> 2, m = it & 3;
;       if (it + 1 < 8) EPI_LOAD_ROW(it + 1, hn, ln_, pq);
;       const int row = row0 + ai * 128 + m * 16;
;       float sq = 0.f;
; #pragma unroll
;       for (int bj = 0; bj < 2; ++bj) {
;         const size_t idx = (size_t)row * 1024 + lcp + bj * 32;
;         const uint32_t hw[4] = {hc[bj].x, hc[bj].y, hc[bj].z, hc[bj].w};
;         const uint32_t lw[4] = {lc[bj].x, lc[bj].y, lc[bj].z, lc[bj].w};
;         const uint32_t pw[4] = {pc[bj].x, pc[bj].y, pc[bj].z, pc[bj].w};
;         uint32_t ho[4], lo_[4];
; #pragma unroll
;         for (int n = 0; n < 2; ++n) {
;           f32x4 xv;
;           xv[0] = __uint_as_float(hw[2 * n] << 16) + __uint_as_float(lw[2 * n] << 16);
;           xv[1] = __uint_as_float(hw[2 * n] & 0xffff0000u) + __uint_as_float(lw[2 * n] & 0xffff0000u);
;           xv[2] = __uint_as_float(hw[2 * n + 1] << 16) + __uint_as_float(lw[2 * n + 1] << 16);
;           xv[3] = __uint_as_float(hw[2 * n + 1] & 0xffff0000u) + __uint_as_float(lw[2 * n + 1] & 0xffff0000u);
;           const f32x4 a = acc[ai][bj][m][n];
;           f32x4 v;
;           if constexpr (EPI == EPI_PLEGATE) {
;             const float rs = rsr[ai][m], rpe = rper[ai][m];
;             const float pv[4] = {__uint_as_float(pw[2 * n] << 16), __uint_as_float(pw[2 * n] & 0xffff0000u),
;                                  __uint_as_float(pw[2 * n + 1] << 16), __uint_as_float(pw[2 * n + 1] & 0xffff0000u)};
; #pragma unroll
;             for (int i = 0; i < 4; ++i) v[i] = xv[i] + sigmoidf_(a[i] * rs) * (pv[i] * rpe);
;           } else {
;             v = xv + a * ea.alpha;
;           }
;           const uint2 hnew = pack4(v);
;           ho[2 * n] = hnew.x; ho[2 * n + 1] = hnew.y;
;           if (ea.xf32_out) {
.LBB0_315:
	s_or_b64 exec, exec, s[8:9]
	v_or_b32_e32 v76, 48, v126
	v_ashrrev_i32_e32 v77, 31, v76
	v_lshlrev_b64 v[32:33], 10, v[76:77]
	v_lshl_add_u64 v[80:81], v[32:33], 0, v[194:195]
	v_lshlrev_b64 v[78:79], 1, v[80:81]
	v_readlane_b32 s8, v251, 32
	v_lshl_add_u64 v[32:33], s[46:47], 0, v[78:79]
	v_lshl_add_u64 v[34:35], s[18:19], 0, v[78:79]
	v_readlane_b32 s9, v251, 33
	s_waitcnt vmcnt(4)
	v_and_b32_e32 v75, 0xffff0000, v92
	v_lshlrev_b32_e32 v102, 16, v84
	v_lshl_add_u64 v[72:73], s[8:9], 0, v[78:79]
	global_load_dwordx4 v[64:67], v[32:33], off
	global_load_dwordx4 v[40:43], v[32:33], off offset:64
	global_load_dwordx4 v[68:71], v[34:35], off
	global_load_dwordx4 v[44:47], v[34:35], off offset:64
	global_load_dwordx4 v[48:51], v[72:73], off
	s_nop 0
	global_load_dwordx4 v[32:35], v[72:73], off offset:64
	v_fmamk_f32 v72, v211, 0x3a800000, v218
	v_mul_f32_e32 v73, 0x4b800000, v72
	v_cmp_gt_f32_e32 vcc, s26, v72
	v_and_b32_e32 v103, 0xffff0000, v84
	v_lshlrev_b32_e32 v84, 16, v85
	v_cndmask_b32_e32 v72, v72, v73, vcc
	v_fmamk_f32 v73, v216, 0x3a800000, v218
	v_rsq_f32_e32 v72, v72
	v_mul_f32_e32 v74, 0x4b800000, v73
	v_cmp_gt_f32_e64 s[8:9], s26, v73
	v_and_b32_e32 v85, 0xffff0000, v85
	s_mov_b64 s[36:37], -1
	v_cndmask_b32_e64 v73, v73, v74, s[8:9]
	v_rsq_f32_e32 v73, v73
	v_mul_f32_e32 v74, 0x45800000, v72
	v_cndmask_b32_e32 v100, v72, v74, vcc
	v_mul_f32_e32 v30, v100, v30
	v_mul_f32_e32 v72, 0x45800000, v73
	v_cndmask_b32_e64 v82, v73, v72, s[8:9]
	v_lshlrev_b32_e32 v72, 16, v88
	v_lshlrev_b32_e32 v74, 16, v92
	v_and_b32_e32 v73, 0xffff0000, v88
	v_mul_f32_e32 v28, v100, v28
	v_mul_f32_e32 v29, v100, v29
	v_mul_f32_e32 v30, 0xbfb8aa3b, v30
	v_mul_f32_e32 v28, 0xbfb8aa3b, v28
	v_mul_f32_e32 v29, 0xbfb8aa3b, v29
	v_pk_add_f32 v[72:73], v[72:73], v[74:75]
	v_exp_f32_e32 v74, v30
	v_mul_f32_e32 v30, v100, v31
	v_exp_f32_e32 v28, v28
	v_exp_f32_e32 v29, v29
	v_mul_f32_e32 v30, 0xbfb8aa3b, v30
	v_exp_f32_e32 v75, v30
	v_add_f32_e32 v28, 1.0, v28
	v_add_f32_e32 v29, 1.0, v29
	v_rcp_f32_e32 v28, v28
	v_rcp_f32_e32 v29, v29
	v_add_f32_e32 v74, 1.0, v74
	v_add_f32_e32 v75, 1.0, v75
	v_rcp_f32_e32 v74, v74
	v_rcp_f32_e32 v75, v75
	v_lshlrev_b32_e32 v88, 16, v89
	v_lshlrev_b32_e32 v92, 16, v93
	v_and_b32_e32 v89, 0xffff0000, v89
	v_and_b32_e32 v93, 0xffff0000, v93
	v_pk_mul_f32 v[30:31], v[82:83], v[102:103] op_sel_hi:[0,1]
	v_pk_fma_f32 v[28:29], v[28:29], v[30:31], v[72:73]
	v_pk_add_f32 v[30:31], v[88:89], v[92:93]
	v_pk_mul_f32 v[72:73], v[82:83], v[84:85] op_sel_hi:[0,1]
	v_pk_fma_f32 v[30:31], v[74:75], v[72:73], v[30:31]
	s_and_b64 vcc, exec, s[4:5]
	v_cvt_pk_bf16_f32 v72, v28, v29
	v_cvt_pk_bf16_f32 v73, v30, v31
	s_cbranch_vccnz .LBB0_317
	v_lshl_add_u64 v[74:75], v[116:117], 2, s[88:89]
	s_mov_b64 s[36:37], 0
	s_mov_b64 s[8:9], s[88:89]
	global_store_dwordx4 v[74:75], v[28:31], off

; __device__ __forceinline__ float sigmoidf_(float x) { return __builtin_amdgcn_rcpf(1.f + __expf(-x)); }
; __device__ __forceinline__ float rstd_of(float ssv) { return rsqrtf(ssv * (1.f / 1024.f) + EPS); }
; template <int EPI>
; __device__ __forceinline__ void gemm_epilogue(const f32x4 (&acc)[2][2][4][2], const Unit& u, int wr, int wc, int fr, int fq,
;                                               const EpiArgs& ea, const float (&rs_pre)[2][4]) {
;     ...
;         for (int m = 0; m < 4; ++m) rper[ai][m] = ea.aux_f0[row0 + ai * 128 + m * 16];
; #pragma unroll
;       for (int ai = 0; ai < 2; ++ai)
; #pragma unroll
;         for (int m = 0; m < 4; ++m) rper[ai][m] = rstd_of(rper[ai][m]);
;     ...
;           xv[0] = __uint_as_float(hw[2 * n] << 16) + __uint_as_float(lw[2 * n] << 16);
;           xv[1] = __uint_as_float(hw[2 * n] & 0xffff0000u) + __uint_as_float(lw[2 * n] & 0xffff0000u);
;           xv[2] = __uint_as_float(hw[2 * n + 1] << 16) + __uint_as_float(lw[2 * n + 1] << 16);
;           xv[3] = __uint_as_float(hw[2 * n + 1] & 0xffff0000u) + __uint_as_float(lw[2 * n + 1] & 0xffff0000u);
;           const f32x4 a = acc[ai][bj][m][n];
;           f32x4 v;
;           if constexpr (EPI == EPI_PLEGATE) {
;             const float rs = rsr[ai][m], rpe = rper[ai][m];
;             const float pv[4] = {__uint_as_float(pw[2 * n] << 16), __uint_as_float(pw[2 * n] & 0xffff0000u),
;                                  __uint_as_float(pw[2 * n + 1] << 16), __uint_as_float(pw[2 * n + 1] & 0xffff0000u)};
; #pragma unroll
;             for (int i = 0; i < 4; ++i) v[i] = xv[i] + sigmoidf_(a[i] * rs) * (pv[i] * rpe);
;           } else {
;             v = xv + a * ea.alpha;
;           }
;           const uint2 hnew = pack4(v);
;           ho[2 * n] = hnew.x; ho[2 * n + 1] = hnew.y;
;           if (ea.xf32_out) {
;             *reinterpret_cast<f32x4*>(ea.xf32_out + idx + 4 * n) = v;
.LBB0_338:
	s_or_b64 exec, exec, s[8:9]
	v_fmamk_f32 v16, v210, 0x3a800000, v218
	v_cmp_gt_f32_e32 vcc, s26, v16
	v_mul_f32_e32 v17, 0x4b800000, v16
	s_waitcnt vmcnt(4)
	v_lshlrev_b32_e32 v18, 16, v68
	v_cndmask_b32_e32 v16, v16, v17, vcc
	v_rsq_f32_e32 v16, v16
	v_and_b32_e32 v19, 0xffff0000, v68
	v_lshlrev_b32_e32 v28, 16, v48
	v_and_b32_e32 v29, 0xffff0000, v48
	v_mul_f32_e32 v17, 0x45800000, v16
	v_cndmask_b32_e32 v22, v16, v17, vcc
	v_mul_f32_e32 v12, v22, v12
	v_mul_f32_e32 v13, v22, v13
	v_fmamk_f32 v16, v214, 0x3a800000, v218
	v_mul_f32_e32 v12, 0xbfb8aa3b, v12
	v_mul_f32_e32 v13, 0xbfb8aa3b, v13
	v_mul_f32_e32 v14, v22, v14
	v_mul_f32_e32 v15, v22, v15
	v_cmp_gt_f32_e32 vcc, s26, v16
	v_mul_f32_e32 v17, 0x4b800000, v16
	v_exp_f32_e32 v12, v12
	v_exp_f32_e32 v13, v13
	v_mul_f32_e32 v14, 0xbfb8aa3b, v14
	v_mul_f32_e32 v15, 0xbfb8aa3b, v15
	v_cndmask_b32_e32 v16, v16, v17, vcc
	v_exp_f32_e32 v14, v14
	v_exp_f32_e32 v15, v15
	v_rsq_f32_e32 v16, v16
	v_add_f32_e32 v12, 1.0, v12
	v_add_f32_e32 v13, 1.0, v13
	v_rcp_f32_e32 v12, v12
	v_rcp_f32_e32 v13, v13
	v_add_f32_e32 v14, 1.0, v14
	v_add_f32_e32 v15, 1.0, v15
	v_mul_f32_e32 v17, 0x45800000, v16
	v_rcp_f32_e32 v14, v14
	v_rcp_f32_e32 v15, v15
	v_cndmask_b32_e32 v20, v16, v17, vcc
	v_lshlrev_b32_e32 v16, 16, v64
	v_and_b32_e32 v17, 0xffff0000, v64
	v_lshlrev_b32_e32 v24, 16, v65
	v_lshlrev_b32_e32 v26, 16, v69
	v_and_b32_e32 v25, 0xffff0000, v65
	v_and_b32_e32 v27, 0xffff0000, v69
	v_lshlrev_b32_e32 v30, 16, v49
	v_and_b32_e32 v31, 0xffff0000, v49
	v_pk_add_f32 v[16:17], v[16:17], v[18:19]
	v_pk_mul_f32 v[18:19], v[20:21], v[28:29] op_sel_hi:[0,1]
	v_pk_fma_f32 v[12:13], v[12:13], v[18:19], v[16:17]
	v_pk_add_f32 v[16:17], v[24:25], v[26:27]
	v_pk_mul_f32 v[18:19], v[20:21], v[30:31] op_sel_hi:[0,1]
	v_pk_fma_f32 v[14:15], v[14:15], v[18:19], v[16:17]
	s_mov_b64 s[8:9], -1
	s_and_b64 vcc, exec, s[4:5]
	v_cvt_pk_bf16_f32 v16, v12, v13
	v_cvt_pk_bf16_f32 v17, v14, v15
	s_cbranch_vccnz .LBB0_340
	v_lshl_add_u64 v[18:19], v[80:81], 2, s[88:89]
	s_mov_b64 s[8:9], 0
	s_mov_b64 s[4:5], s[88:89]
	global_store_dwordx4 v[18:19], v[12:15], off
